# first barrier round made hierarchical (first arriver per XCC does the single L2 write-back) plus decode SSD conv staging loads issued together
# baseline (speedup 1.0000x reference)
; __global__ void __launch_bounds__(NT) fwd_kernel(Params P) {
;     ...
;   for (int ph = P.ph_lo; ph < P.ph_hi; ++ph) {
;     if (ph > P.ph_lo) grid.sync();
.LBB0_4:
	s_cmp_le_i32 s76, s66
	s_cbranch_scc1 .LBB0_16
	s_waitcnt vmcnt(0)
	s_barrier
	s_mov_b64 s[0:1], exec
	v_readlane_b32 s4, v254, 13
	v_readlane_b32 s5, v254, 14
	s_and_b64 s[4:5], s[0:1], s[4:5]
	s_mov_b64 exec, s[4:5]
	s_cbranch_execz .Lxb_join
	v_readlane_b32 s4, v254, 59
	v_readlane_b32 s5, v254, 60
	s_getreg_b32 s6, hwreg(HW_REG_XCC_ID, 0, 4)
	s_lshl_b32 s6, s6, 2
	s_add_i32 s100, s100, 1
	v_mov_b32_e32 v0, s6
	v_mov_b32_e32 v1, 1
	s_nop 4
	s_cmp_lg_u32 s98, 0
	s_cbranch_scc1 .Lxb_fast
	global_atomic_add v2, v0, v1, s[4:5] offset:192 sc0
	buffer_inv sc1
	s_waitcnt vmcnt(0)
	v_readfirstlane_b32 s6, v2
	s_cmp_lg_u32 s6, 0
	s_cbranch_scc1 .Lxb_c1
	global_atomic_add v2, v65, v1, s[4:5] offset:8 sc0
	s_waitcnt vmcnt(0)

; __global__ void __launch_bounds__(NT) fwd_kernel(Params P) {
;     ...
;   for (int ph = P.ph_lo; ph < P.ph_hi; ++ph) {
;     if (ph > P.ph_lo) grid.sync();
.Lxb_c3:
	global_load_dword v2, v0, s[4:5] offset:192 sc1
	global_load_dword v1, v65, s[4:5] offset:8 sc1
	s_waitcnt vmcnt(0)
	v_readfirstlane_b32 s98, v2
	v_readfirstlane_b32 s99, v1
	v_mov_b32_e32 v1, 1
	s_mov_b32 s8, s99
	s_mov_b32 s10, 0
	s_cmp_lg_u32 s6, 0
	s_cbranch_scc1 .Lxb_w1
	buffer_wbl2 sc1
	s_waitcnt vmcnt(0)
	global_atomic_add v65, v1, s[4:5] offset:12
.Lxb_w1:
	global_load_dword v2, v65, s[4:5] offset:12 sc1
	s_waitcnt vmcnt(0)
	v_readfirstlane_b32 s9, v2
	s_cmp_ge_u32 s9, s8
	s_cbranch_scc1 .Lxb_join
	s_sleep 1
	s_add_i32 s10, s10, 1
	s_cmp_lt_u32 s10, 0x8000
	s_cbranch_scc1 .Lxb_w1
	s_branch .Lxb_join
